# rnn pass 2 gelu evaluated as y*(1-r) with the two exp-argument constants folded (3 VALU ops fewer per element); wait-state pads kept where a transcendental result is consumed next
# baseline (speedup 1.0000x reference)
; DI unsigned pk2(float lo, float hi) { f32x2 v = {lo, hi}; bf16x2_t b = __builtin_convertvector(v, bf16x2_t); return __builtin_bit_cast(unsigned, b); }
; DI float bf1(bf16_t u) { return __uint_as_float(((unsigned)u) << 16); }
; DI float gelu_tanh(float y) { const float z = 0.7978845608028654f * (y + 0.044715f * y * y * y); const float t = 1.0f - 2.0f * __builtin_amdgcn_rcpf(1.0f + __builtin_amdgcn_exp2f(2.0f * LOG2E * z)); return 0.5f * y * (1.0f + t); }
; DI void rnn_phase(LAS unsigned char* lds, bf16_t* P, const bf16_t* WaT, const bf16_t* WiT, const float* convw, const float* convb, const float* ba, const float* bi, const float* lam,
;                   f32x2* sums, unsigned* au, bool fin, int bx, int G, int tid, int wid, int lane) {
;     ...
; #pragma unroll
;             for (int j = 0; j < 16; ++j) { h = av[j] * h + uv[j]; const float o = h * gelu_tanh(bf1(yv[j])); yp[(size_t)j * DIN] = (bf16_t)(pk2(o, 0.f) & 0xffffu); }
;             par ^= 1;
.LBB0_368:
	v_cvt_f32_f16_sdwa v90, v53 dst_sel:DWORD dst_unused:UNUSED_PAD src0_sel:WORD_1
	v_lshl_add_u64 v[32:33], v[0:1], 0, s[10:11]
	v_cvt_f32_f16_sdwa v89, v56 dst_sel:DWORD dst_unused:UNUSED_PAD src0_sel:WORD_1
	s_mov_b64 s[22:23], 0x4400
	v_fmac_f32_e32 v90, v83, v31
	v_lshlrev_b32_e32 v31, 16, v58
	v_mul_f32_e32 v58, 0x3d372713, v31
	v_mul_f32_e32 v58, v58, v31
	v_fma_f32 v58, v58, v31, v31
	v_mul_f32_e32 v58, 0x40135761, v58
	v_exp_f32_e32 v58, v58
	v_fmac_f32_e32 v89, v82, v90
	v_lshl_add_u64 v[28:29], v[0:1], 0, s[22:23]
	v_add_f32_e32 v58, 1.0, v58
	v_rcp_f32_e32 v58, v58
	v_cvt_f32_f16_sdwa v88, v60 dst_sel:DWORD dst_unused:UNUSED_PAD src0_sel:WORD_1
	s_mov_b64 s[22:23], 0x8000
	v_lshl_add_u64 v[26:27], v[0:1], 0, s[22:23]
	v_sub_f32_e32 v58, 1.0, v58
	v_mul_f32_e32 v31, v31, v58
	v_mul_f32_e32 v31, v31, v90
	v_cvt_pk_bf16_f32 v31, v31, s0
	flat_store_short v[32:33], v31
	v_lshlrev_b32_e32 v31, 16, v55
	v_mul_f32_e32 v32, 0x3d372713, v31
	v_mul_f32_e32 v32, v32, v31
	v_fma_f32 v32, v32, v31, v31
	v_mul_f32_e32 v32, 0x40135761, v32
	v_exp_f32_e32 v32, v32
	v_fmac_f32_e32 v88, v80, v89
	v_cvt_f32_f16_sdwa v87, v62 dst_sel:DWORD dst_unused:UNUSED_PAD src0_sel:WORD_1
	v_add_f32_e32 v32, 1.0, v32
	v_rcp_f32_e32 v32, v32
	s_mov_b64 s[22:23], 0xbc00
	v_fmac_f32_e32 v87, v79, v88
	v_lshl_add_u64 v[24:25], v[0:1], 0, s[22:23]
	v_sub_f32_e32 v32, 1.0, v32
	v_mul_f32_e32 v31, v31, v32
	v_mul_f32_e32 v31, v31, v89
	v_cvt_pk_bf16_f32 v31, v31, s0
	flat_store_short v[28:29], v31
	v_lshlrev_b32_e32 v28, 16, v51
	v_mul_f32_e32 v29, 0x3d372713, v28
	v_mul_f32_e32 v29, v29, v28
	v_fma_f32 v29, v29, v28, v28
	v_mul_f32_e32 v29, 0x40135761, v29
	v_exp_f32_e32 v29, v29
	v_cvt_f32_f16_sdwa v86, v63 dst_sel:DWORD dst_unused:UNUSED_PAD src0_sel:WORD_1
	s_mov_b64 s[22:23], 0xf800
	v_add_f32_e32 v29, 1.0, v29
	v_rcp_f32_e32 v29, v29
	v_fmac_f32_e32 v86, v76, v87
	v_lshl_add_u64 v[22:23], v[0:1], 0, s[22:23]
	v_cvt_f32_f16_sdwa v85, v65 dst_sel:DWORD dst_unused:UNUSED_PAD src0_sel:WORD_1
	v_sub_f32_e32 v29, 1.0, v29
	v_mul_f32_e32 v28, v28, v29
	v_mul_f32_e32 v28, v28, v88
	v_cvt_pk_bf16_f32 v28, v28, s0
	flat_store_short v[26:27], v28
	v_lshlrev_b32_e32 v26, 16, v49
	v_mul_f32_e32 v27, 0x3d372713, v26
	v_mul_f32_e32 v27, v27, v26
	v_fma_f32 v27, v27, v26, v26
	v_mul_f32_e32 v27, 0x40135761, v27
	v_exp_f32_e32 v27, v27
	v_fmac_f32_e32 v85, v72, v86
	s_mov_b64 s[22:23], 0x13400
	v_add_f32_e32 v27, 1.0, v27
	v_rcp_f32_e32 v27, v27
	v_lshl_add_u64 v[20:21], v[0:1], 0, s[22:23]
	v_cvt_f32_f16_sdwa v84, v67 dst_sel:DWORD dst_unused:UNUSED_PAD src0_sel:WORD_1
	s_mov_b64 s[22:23], 0x17000
	v_sub_f32_e32 v27, 1.0, v27
	v_mul_f32_e32 v26, v26, v27
	v_mul_f32_e32 v26, v26, v87
	v_cvt_pk_bf16_f32 v26, v26, s0
	flat_store_short v[24:25], v26
	v_lshlrev_b32_e32 v24, 16, v47
	v_mul_f32_e32 v25, 0x3d372713, v24
	v_mul_f32_e32 v25, v25, v24
	v_fma_f32 v25, v25, v24, v24
	v_mul_f32_e32 v25, 0x40135761, v25
	v_exp_f32_e32 v25, v25
	v_fmac_f32_e32 v84, v66, v85
	v_lshl_add_u64 v[18:19], v[0:1], 0, s[22:23]
	v_add_f32_e32 v25, 1.0, v25
	v_rcp_f32_e32 v25, v25
	v_cvt_f32_f16_sdwa v68, v68 dst_sel:DWORD dst_unused:UNUSED_PAD src0_sel:WORD_1
	s_mov_b64 s[22:23], 0x1ac00
	v_lshl_add_u64 v[16:17], v[0:1], 0, s[22:23]
	v_sub_f32_e32 v25, 1.0, v25
	v_mul_f32_e32 v24, v24, v25
	v_mul_f32_e32 v24, v24, v86
	v_cvt_pk_bf16_f32 v24, v24, s0
	flat_store_short v[22:23], v24
	v_lshlrev_b32_e32 v22, 16, v44
	v_mul_f32_e32 v23, 0x3d372713, v22
	v_mul_f32_e32 v23, v23, v22
	v_fma_f32 v23, v23, v22, v22
	v_mul_f32_e32 v23, 0x40135761, v23
	v_exp_f32_e32 v23, v23
	v_fmac_f32_e32 v68, v61, v84
	v_cvt_f32_f16_sdwa v67, v69 dst_sel:DWORD dst_unused:UNUSED_PAD src0_sel:WORD_1
	v_add_f32_e32 v23, 1.0, v23
	v_rcp_f32_e32 v23, v23
	s_mov_b64 s[22:23], 0x1e800
	v_fmac_f32_e32 v67, v59, v68
	v_lshl_add_u64 v[14:15], v[0:1], 0, s[22:23]
	v_sub_f32_e32 v23, 1.0, v23
	v_mul_f32_e32 v22, v22, v23
	v_mul_f32_e32 v22, v22, v85
	v_cvt_pk_bf16_f32 v22, v22, s0
	flat_store_short v[20:21], v22
	v_lshlrev_b32_e32 v20, 16, v43
	v_mul_f32_e32 v21, 0x3d372713, v20
	v_mul_f32_e32 v21, v21, v20
	v_fma_f32 v21, v21, v20, v20
	v_mul_f32_e32 v21, 0x40135761, v21
	v_exp_f32_e32 v21, v21
	v_cvt_f32_f16_sdwa v65, v70 dst_sel:DWORD dst_unused:UNUSED_PAD src0_sel:WORD_1
	s_mov_b64 s[22:23], 0x22400
	v_add_f32_e32 v21, 1.0, v21
	v_rcp_f32_e32 v21, v21
	v_fmac_f32_e32 v65, v57, v67
	v_lshl_add_u64 v[12:13], v[0:1], 0, s[22:23]
	v_cvt_f32_f16_sdwa v63, v71 dst_sel:DWORD dst_unused:UNUSED_PAD src0_sel:WORD_1
	v_sub_f32_e32 v21, 1.0, v21
	v_mul_f32_e32 v20, v20, v21
	v_mul_f32_e32 v20, v20, v84
	v_cvt_pk_bf16_f32 v20, v20, s0
; DI unsigned pk2(float lo, float hi) { f32x2 v = {lo, hi}; bf16x2_t b = __builtin_convertvector(v, bf16x2_t); return __builtin_bit_cast(unsigned, b); }
; DI float bf1(bf16_t u) { return __uint_as_float(((unsigned)u) << 16); }
; DI float gelu_tanh(float y) { const float z = 0.7978845608028654f * (y + 0.044715f * y * y * y); const float t = 1.0f - 2.0f * __builtin_amdgcn_rcpf(1.0f + __builtin_amdgcn_exp2f(2.0f * LOG2E * z)); return 0.5f * y * (1.0f + t); }
; DI void rnn_phase(LAS unsigned char* lds, bf16_t* P, const bf16_t* WaT, const bf16_t* WiT, const float* convw, const float* convb, const float* ba, const float* bi, const float* lam,
;                   f32x2* sums, unsigned* au, bool fin, int bx, int G, int tid, int wid, int lane) {
;     ...
; #pragma unroll
;             for (int j = 0; j < 16; ++j) { h = av[j] * h + uv[j]; const float o = h * gelu_tanh(bf1(yv[j])); yp[(size_t)j * DIN] = (bf16_t)(pk2(o, 0.f) & 0xffffu); }
;             par ^= 1;
	flat_store_short v[18:19], v20
	v_lshlrev_b32_e32 v18, 16, v42
	v_mul_f32_e32 v19, 0x3d372713, v18
	v_mul_f32_e32 v19, v19, v18
	v_fma_f32 v19, v19, v18, v18
	v_mul_f32_e32 v19, 0x40135761, v19
	v_exp_f32_e32 v19, v19
	v_fmac_f32_e32 v63, v54, v65
	s_mov_b64 s[22:23], 0x26000
	v_add_f32_e32 v19, 1.0, v19
	v_rcp_f32_e32 v19, v19
	v_lshl_add_u64 v[10:11], v[0:1], 0, s[22:23]
	v_cvt_f32_f16_sdwa v62, v73 dst_sel:DWORD dst_unused:UNUSED_PAD src0_sel:WORD_1
	s_mov_b64 s[22:23], 0x29c00
	v_sub_f32_e32 v19, 1.0, v19
	v_mul_f32_e32 v18, v18, v19
	v_mul_f32_e32 v18, v18, v68
	v_cvt_pk_bf16_f32 v18, v18, s0
	flat_store_short v[16:17], v18
	v_lshlrev_b32_e32 v16, 16, v41
	v_mul_f32_e32 v17, 0x3d372713, v16
	v_mul_f32_e32 v17, v17, v16
	v_fma_f32 v17, v17, v16, v16
	v_mul_f32_e32 v17, 0x40135761, v17
	v_exp_f32_e32 v17, v17
	v_fmac_f32_e32 v62, v52, v63
	v_lshl_add_u64 v[8:9], v[0:1], 0, s[22:23]
	v_add_f32_e32 v17, 1.0, v17
	v_rcp_f32_e32 v17, v17
	v_cvt_f32_f16_sdwa v60, v74 dst_sel:DWORD dst_unused:UNUSED_PAD src0_sel:WORD_1
	s_mov_b64 s[22:23], 0x2d800
	v_lshl_add_u64 v[6:7], v[0:1], 0, s[22:23]
	v_sub_f32_e32 v17, 1.0, v17
	v_mul_f32_e32 v16, v16, v17
	v_mul_f32_e32 v16, v16, v67
	v_cvt_pk_bf16_f32 v16, v16, s0
	flat_store_short v[14:15], v16
	v_lshlrev_b32_e32 v14, 16, v40
	v_mul_f32_e32 v15, 0x3d372713, v14
	v_mul_f32_e32 v15, v15, v14
	v_fma_f32 v15, v15, v14, v14
	v_mul_f32_e32 v15, 0x40135761, v15
	v_exp_f32_e32 v15, v15
	v_fmac_f32_e32 v60, v50, v62
	v_cvt_f32_f16_sdwa v56, v75 dst_sel:DWORD dst_unused:UNUSED_PAD src0_sel:WORD_1
	v_add_f32_e32 v15, 1.0, v15
	v_rcp_f32_e32 v15, v15
	s_mov_b64 s[22:23], 0x31400
	v_fmac_f32_e32 v56, v48, v60
	v_lshl_add_u64 v[4:5], v[0:1], 0, s[22:23]
	v_sub_f32_e32 v15, 1.0, v15
	v_mul_f32_e32 v14, v14, v15
	v_mul_f32_e32 v14, v14, v65
	v_cvt_pk_bf16_f32 v14, v14, s0
	flat_store_short v[12:13], v14
	v_lshlrev_b32_e32 v12, 16, v39
	v_mul_f32_e32 v13, 0x3d372713, v12
	v_mul_f32_e32 v13, v13, v12
	v_fma_f32 v13, v13, v12, v12
	v_mul_f32_e32 v13, 0x40135761, v13
	v_exp_f32_e32 v13, v13
	v_cvt_f32_f16_sdwa v53, v77 dst_sel:DWORD dst_unused:UNUSED_PAD src0_sel:WORD_1
	s_mov_b64 s[22:23], 0x35000
	v_add_f32_e32 v13, 1.0, v13
	v_rcp_f32_e32 v13, v13
	v_fmac_f32_e32 v53, v46, v56
	v_lshl_add_u64 v[2:3], v[0:1], 0, s[22:23]
	v_cvt_f32_f16_sdwa v30, v78 dst_sel:DWORD dst_unused:UNUSED_PAD src0_sel:WORD_1
	v_sub_f32_e32 v13, 1.0, v13
	v_mul_f32_e32 v12, v12, v13
	v_mul_f32_e32 v12, v12, v63
	v_cvt_pk_bf16_f32 v12, v12, s0
	flat_store_short v[10:11], v12
	v_lshlrev_b32_e32 v10, 16, v38
	v_mul_f32_e32 v11, 0x3d372713, v10
	v_mul_f32_e32 v11, v11, v10
	v_fma_f32 v11, v11, v10, v10
	v_mul_f32_e32 v11, 0x40135761, v11
	v_exp_f32_e32 v11, v11
	v_fmac_f32_e32 v30, v45, v53
	s_mov_b64 s[22:23], 0x38c00
	v_add_f32_e32 v11, 1.0, v11
	v_rcp_f32_e32 v11, v11
	s_xor_b32 s20, s20, 1
	s_add_i32 s1, s1, s29
	v_lshl_add_u64 v[0:1], v[0:1], 0, s[22:23]
	v_sub_f32_e32 v11, 1.0, v11
	v_mul_f32_e32 v10, v10, v11
	v_mul_f32_e32 v10, v10, v62
	v_cvt_pk_bf16_f32 v10, v10, s0
	flat_store_short v[8:9], v10
	v_lshlrev_b32_e32 v8, 16, v37
	v_mul_f32_e32 v9, 0x3d372713, v8
	v_mul_f32_e32 v9, v9, v8
	v_fma_f32 v9, v9, v8, v8
	v_mul_f32_e32 v9, 0x40135761, v9
	v_exp_f32_e32 v9, v9
	s_cmpk_gt_i32 s1, 0x7ff
	v_add_f32_e32 v9, 1.0, v9
	v_rcp_f32_e32 v9, v9
	s_nop 0
	v_sub_f32_e32 v9, 1.0, v9
	v_mul_f32_e32 v8, v8, v9
	v_mul_f32_e32 v8, v8, v60
	v_cvt_pk_bf16_f32 v8, v8, s0
	flat_store_short v[6:7], v8
	v_lshlrev_b32_e32 v6, 16, v36
	v_mul_f32_e32 v7, 0x3d372713, v6
	v_mul_f32_e32 v7, v7, v6
	v_fma_f32 v7, v7, v6, v6
	v_mul_f32_e32 v7, 0x40135761, v7
	v_exp_f32_e32 v7, v7
	s_nop 0
	v_add_f32_e32 v7, 1.0, v7
	v_rcp_f32_e32 v7, v7
	s_nop 0
	v_sub_f32_e32 v7, 1.0, v7
	v_mul_f32_e32 v6, v6, v7
	v_mul_f32_e32 v6, v6, v56
	v_cvt_pk_bf16_f32 v6, v6, s0
	flat_store_short v[4:5], v6
	v_lshlrev_b32_e32 v4, 16, v35
	v_mul_f32_e32 v5, 0x3d372713, v4
	v_mul_f32_e32 v5, v5, v4
	v_fma_f32 v5, v5, v4, v4
	v_mul_f32_e32 v5, 0x40135761, v5
	v_exp_f32_e32 v5, v5
	s_nop 0
	v_add_f32_e32 v5, 1.0, v5
	v_rcp_f32_e32 v5, v5
	s_nop 0
	v_sub_f32_e32 v5, 1.0, v5
	v_mul_f32_e32 v4, v4, v5
	v_mul_f32_e32 v4, v4, v53
	v_cvt_pk_bf16_f32 v4, v4, s0
	flat_store_short v[2:3], v4
	v_lshlrev_b32_e32 v2, 16, v34
	v_mul_f32_e32 v3, 0x3d372713, v2
	v_mul_f32_e32 v3, v3, v2
	v_fma_f32 v3, v3, v2, v2
	v_mul_f32_e32 v3, 0x40135761, v3
	v_exp_f32_e32 v3, v3
	s_nop 0
	v_add_f32_e32 v3, 1.0, v3
	v_rcp_f32_e32 v3, v3
	s_nop 0
	v_sub_f32_e32 v3, 1.0, v3
	v_mul_f32_e32 v2, v2, v3
	v_mul_f32_e32 v2, v2, v30
	v_cvt_pk_bf16_f32 v2, v2, s0
	flat_store_short v[0:1], v2
	s_cbranch_scc1 .LBB0_387
